# attention PV: batch-3 V fragment reads issued with batch 2, per-batch lgkmcnt waits (on top of QK fragment-order MFMAs and whole-round phase-0 offload)
# baseline (speedup 1.0000x reference)
.LBB0_1126:
	v_sub_f32_e32 v128, v128, v143
	v_exp_f32_e32 v128, v128
	v_sub_f32_e32 v129, v129, v143
	v_exp_f32_e32 v129, v129
	v_sub_f32_e32 v130, v130, v143
	v_exp_f32_e32 v130, v130
	v_sub_f32_e32 v131, v131, v143
	v_exp_f32_e32 v131, v131
	v_sub_f32_e32 v124, v124, v143
	v_add_f32_e32 v165, 0, v128
	v_exp_f32_e32 v124, v124
	v_sub_f32_e32 v125, v125, v143
	v_add_f32_e32 v165, v129, v165
	v_exp_f32_e32 v125, v125
	v_sub_f32_e32 v126, v126, v143
	v_add_f32_e32 v165, v130, v165
	v_exp_f32_e32 v126, v126
	v_sub_f32_e32 v127, v127, v143
	v_add_f32_e32 v165, v131, v165
	v_exp_f32_e32 v127, v127
	v_sub_f32_e32 v120, v120, v143
	v_add_f32_e32 v165, v124, v165
	v_exp_f32_e32 v166, v120
	v_sub_f32_e32 v120, v121, v143
	v_add_f32_e32 v165, v125, v165
	v_exp_f32_e32 v167, v120
	v_sub_f32_e32 v120, v122, v143
	v_add_f32_e32 v165, v126, v165
	v_exp_f32_e32 v168, v120
	v_sub_f32_e32 v120, v123, v143
	v_add_f32_e32 v165, v127, v165
	v_exp_f32_e32 v123, v120
	v_sub_f32_e32 v116, v116, v143
	v_add_f32_e32 v120, v166, v165
	v_exp_f32_e32 v165, v116
	v_sub_f32_e32 v116, v117, v143
	v_add_f32_e32 v120, v167, v120
	v_exp_f32_e32 v117, v116
	v_sub_f32_e32 v116, v118, v143
	v_add_f32_e32 v120, v168, v120
	v_exp_f32_e32 v169, v116
	v_sub_f32_e32 v116, v119, v143
	v_add_f32_e32 v120, v123, v120
	v_exp_f32_e32 v170, v116
	v_add_f32_e32 v116, v165, v120
	v_add_f32_e32 v116, v117, v116
	v_add_f32_e32 v116, v169, v116
	v_add_f32_e32 v116, v170, v116
	v_fmac_f32_e32 v116, v1, v2
	v_cvt_pk_bf16_f32 v118, v128, v129
	v_cvt_pk_bf16_f32 v119, v130, v131
	v_cvt_pk_bf16_f32 v120, v124, v125
	v_cvt_pk_bf16_f32 v121, v126, v127
	v_cvt_pk_bf16_f32 v122, v166, v167
	v_cvt_pk_bf16_f32 v123, v168, v123
	v_cvt_pk_bf16_f32 v124, v165, v117
	v_cvt_pk_bf16_f32 v125, v169, v170
	s_waitcnt lgkmcnt(0)
	v_mfma_f32_16x16x32_bf16 v[80:83], v[100:103], v[118:121], v[80:83]
	v_mfma_f32_16x16x32_bf16 v[76:79], v[88:91], v[118:121], v[76:79]
	v_mfma_f32_16x16x32_bf16 v[72:75], v[92:95], v[118:121], v[72:75]
	v_mfma_f32_16x16x32_bf16 v[68:71], v[84:87], v[118:121], v[68:71]
	v_mfma_f32_16x16x32_bf16 v[80:83], v[112:115], v[122:125], v[80:83]
	v_mfma_f32_16x16x32_bf16 v[76:79], v[104:107], v[122:125], v[76:79]
	v_mfma_f32_16x16x32_bf16 v[72:75], v[108:111], v[122:125], v[72:75]
	v_mfma_f32_16x16x32_bf16 v[68:71], v[96:99], v[122:125], v[68:71]
	ds_read_b128 v[84:87], v3 offset:16384
	ds_read_b128 v[88:91], v3 offset:18432
	ds_read_b128 v[92:95], v145 offset:16384
	ds_read_b128 v[96:99], v145 offset:18432
	ds_read_b128 v[100:103], v3 offset:20480
	ds_read_b128 v[104:107], v3 offset:22528
	ds_read_b128 v[108:111], v145 offset:20480
	ds_read_b128 v[112:115], v145 offset:22528
	ds_read_b128 v[126:129], v3 offset:24576
	ds_read_b128 v[166:169], v3 offset:26624
	ds_read_b128 v[170:173], v145 offset:24576
	ds_read_b128 v[174:177], v145 offset:26624
	ds_read_b128 v[178:181], v3 offset:28672
	ds_read_b128 v[182:185], v3 offset:30720
	ds_read_b128 v[186:189], v145 offset:28672
	ds_read_b128 v[190:193], v145 offset:30720
	v_mfma_f32_16x16x32_bf16 v[64:67], v[194:197], v[118:121], v[64:67]
	v_mfma_f32_16x16x32_bf16 v[60:63], v[198:201], v[118:121], v[60:63]
	v_mfma_f32_16x16x32_bf16 v[56:59], v[210:213], v[118:121], v[56:59]
	v_mfma_f32_16x16x32_bf16 v[52:55], v[214:217], v[118:121], v[52:55]
	v_mfma_f32_16x16x32_bf16 v[64:67], v[202:205], v[122:125], v[64:67]
	v_mfma_f32_16x16x32_bf16 v[60:63], v[206:209], v[122:125], v[60:63]
	v_mfma_f32_16x16x32_bf16 v[56:59], v[218:221], v[122:125], v[56:59]
	v_mfma_f32_16x16x32_bf16 v[52:55], v[222:225], v[122:125], v[52:55]
	s_waitcnt lgkmcnt(8)
	v_mfma_f32_16x16x32_bf16 v[48:51], v[84:87], v[118:121], v[48:51]
	v_mfma_f32_16x16x32_bf16 v[44:47], v[88:91], v[118:121], v[44:47]
	v_mfma_f32_16x16x32_bf16 v[40:43], v[100:103], v[118:121], v[40:43]
	v_mfma_f32_16x16x32_bf16 v[36:39], v[104:107], v[118:121], v[36:39]
	v_mfma_f32_16x16x32_bf16 v[48:51], v[92:95], v[122:125], v[48:51]
	v_mfma_f32_16x16x32_bf16 v[44:47], v[96:99], v[122:125], v[44:47]
	v_mfma_f32_16x16x32_bf16 v[40:43], v[108:111], v[122:125], v[40:43]
	v_mfma_f32_16x16x32_bf16 v[36:39], v[112:115], v[122:125], v[36:39]
	s_waitcnt lgkmcnt(0)
	v_mfma_f32_16x16x32_bf16 v[32:35], v[126:129], v[118:121], v[32:35]
	v_mfma_f32_16x16x32_bf16 v[28:31], v[166:169], v[118:121], v[28:31]
	v_mfma_f32_16x16x32_bf16 v[24:27], v[178:181], v[118:121], v[24:27]
	v_mfma_f32_16x16x32_bf16 v[20:23], v[182:185], v[118:121], v[20:23]
	v_mfma_f32_16x16x32_bf16 v[32:35], v[170:173], v[122:125], v[32:35]
	v_mfma_f32_16x16x32_bf16 v[28:31], v[174:177], v[122:125], v[28:31]
	v_mfma_f32_16x16x32_bf16 v[24:27], v[186:189], v[122:125], v[24:27]
	v_mfma_f32_16x16x32_bf16 v[20:23], v[190:193], v[122:125], v[20:23]
	s_add_i32 s50, s50, 64
	v_lshl_add_u64 v[148:149], v[148:149], 0, s[60:61]
	s_cmp_eq_u32 s69, s70
	v_lshl_add_u64 v[146:147], v[146:147], 0, s[20:21]
	s_cbranch_scc1 .LBB0_1129
	v_mov_b32_e32 v1, v116
	s_branch .LBB0_1117
